# work queues: wave 0 reads the 8 queue counters with one load before probing other XCD queues and leaves if all are exhausted
# baseline (speedup 1.0000x reference)
.LBB0_519:
	v_readfirstlane_b32 s98, v210
	s_cmp_lg_u32 s98, 0
	s_cbranch_scc1 .LBB0_592
	s_cmp_lg_u32 s18, 0
	s_cbranch_scc1 .Lq4_scan
	v_and_b32_e32 v0, 7, v210
	v_add_lshl_u32 v0, v0, s92, 8
	global_load_dword v1, v0, s[84:85] sc1
	s_waitcnt vmcnt(0)
	v_cmp_gt_u32_e32 vcc, 0x180, v1
	s_and_b32 s99, vcc_lo, 0xff
	s_cmp_eq_u32 s99, 0
	s_cbranch_scc1 .LBB0_592

.LBB0_665:
	v_readfirstlane_b32 s98, v210
	s_cmp_lg_u32 s98, 0
	s_cbranch_scc1 .LBB0_706
	s_cmp_lg_u32 s20, 0
	s_cbranch_scc1 .Lq5_scan
	v_and_b32_e32 v0, 7, v210
	v_add_lshl_u32 v0, v0, s92, 8
	global_load_dword v1, v0, s[84:85] offset:2048 sc1
	s_waitcnt vmcnt(0)
	v_cmp_gt_u32_e32 vcc, 0x200, v1
	s_and_b32 s99, vcc_lo, 0xff
	s_cmp_eq_u32 s99, 0
	s_cbranch_scc1 .LBB0_706
